# sparse attention softmax: subtract-max and row-sum done with packed f32 adds (16+16 ops instead of 32+33), same arithmetic
# speedup vs baseline: 1.0079x; 1.0079x over previous
.LBB0_56:
	v_pk_add_f32 v[66:67], v[66:67], v[98:99] op_sel:[0,1] op_sel_hi:[1,1] neg_lo:[0,1] neg_hi:[0,1]
	v_pk_add_f32 v[82:83], v[82:83], v[98:99] op_sel:[0,1] op_sel_hi:[1,1] neg_lo:[0,1] neg_hi:[0,1]
	v_exp_f32_e32 v66, v66
	v_exp_f32_e32 v67, v67
	v_exp_f32_e32 v82, v82
	v_exp_f32_e32 v83, v83
	v_pk_add_f32 v[68:69], v[68:69], v[98:99] op_sel:[0,1] op_sel_hi:[1,1] neg_lo:[0,1] neg_hi:[0,1]
	v_pk_add_f32 v[84:85], v[84:85], v[98:99] op_sel:[0,1] op_sel_hi:[1,1] neg_lo:[0,1] neg_hi:[0,1]
	v_exp_f32_e32 v68, v68
	v_exp_f32_e32 v69, v69
	v_exp_f32_e32 v84, v84
	v_exp_f32_e32 v85, v85
	v_pk_add_f32 v[100:101], v[66:67], v[82:83]
	v_pk_add_f32 v[70:71], v[70:71], v[98:99] op_sel:[0,1] op_sel_hi:[1,1] neg_lo:[0,1] neg_hi:[0,1]
	v_pk_add_f32 v[86:87], v[86:87], v[98:99] op_sel:[0,1] op_sel_hi:[1,1] neg_lo:[0,1] neg_hi:[0,1]
	v_exp_f32_e32 v70, v70
	v_exp_f32_e32 v71, v71
	v_exp_f32_e32 v86, v86
	v_exp_f32_e32 v87, v87
	v_pk_add_f32 v[100:101], v[100:101], v[68:69]
	v_pk_add_f32 v[100:101], v[100:101], v[84:85]
	v_pk_add_f32 v[72:73], v[72:73], v[98:99] op_sel:[0,1] op_sel_hi:[1,1] neg_lo:[0,1] neg_hi:[0,1]
	v_pk_add_f32 v[88:89], v[88:89], v[98:99] op_sel:[0,1] op_sel_hi:[1,1] neg_lo:[0,1] neg_hi:[0,1]
	v_exp_f32_e32 v72, v72
	v_exp_f32_e32 v73, v73
	v_exp_f32_e32 v88, v88
	v_exp_f32_e32 v89, v89
	v_pk_add_f32 v[100:101], v[100:101], v[70:71]
	v_pk_add_f32 v[100:101], v[100:101], v[86:87]
	v_pk_add_f32 v[74:75], v[74:75], v[98:99] op_sel:[0,1] op_sel_hi:[1,1] neg_lo:[0,1] neg_hi:[0,1]
	v_pk_add_f32 v[90:91], v[90:91], v[98:99] op_sel:[0,1] op_sel_hi:[1,1] neg_lo:[0,1] neg_hi:[0,1]
	v_exp_f32_e32 v74, v74
	v_exp_f32_e32 v75, v75
	v_exp_f32_e32 v90, v90
	v_exp_f32_e32 v91, v91
	v_pk_add_f32 v[100:101], v[100:101], v[72:73]
	v_pk_add_f32 v[100:101], v[100:101], v[88:89]
	v_pk_add_f32 v[76:77], v[76:77], v[98:99] op_sel:[0,1] op_sel_hi:[1,1] neg_lo:[0,1] neg_hi:[0,1]
	v_pk_add_f32 v[92:93], v[92:93], v[98:99] op_sel:[0,1] op_sel_hi:[1,1] neg_lo:[0,1] neg_hi:[0,1]
	v_exp_f32_e32 v76, v76
	v_exp_f32_e32 v77, v77
	v_exp_f32_e32 v92, v92
	v_exp_f32_e32 v93, v93
	v_pk_add_f32 v[100:101], v[100:101], v[74:75]
	v_pk_add_f32 v[100:101], v[100:101], v[90:91]
	v_pk_add_f32 v[78:79], v[78:79], v[98:99] op_sel:[0,1] op_sel_hi:[1,1] neg_lo:[0,1] neg_hi:[0,1]
	v_pk_add_f32 v[94:95], v[94:95], v[98:99] op_sel:[0,1] op_sel_hi:[1,1] neg_lo:[0,1] neg_hi:[0,1]
	v_exp_f32_e32 v78, v78
	v_exp_f32_e32 v79, v79
	v_exp_f32_e32 v94, v94
	v_exp_f32_e32 v95, v95
	v_pk_add_f32 v[100:101], v[100:101], v[76:77]
	v_pk_add_f32 v[100:101], v[100:101], v[92:93]
	v_pk_add_f32 v[80:81], v[80:81], v[98:99] op_sel:[0,1] op_sel_hi:[1,1] neg_lo:[0,1] neg_hi:[0,1]
	v_pk_add_f32 v[96:97], v[96:97], v[98:99] op_sel:[0,1] op_sel_hi:[1,1] neg_lo:[0,1] neg_hi:[0,1]
	v_exp_f32_e32 v80, v80
	v_exp_f32_e32 v81, v81
	v_exp_f32_e32 v96, v96
	v_exp_f32_e32 v97, v97
	v_pk_add_f32 v[100:101], v[100:101], v[78:79]
	v_pk_add_f32 v[100:101], v[100:101], v[94:95]
	s_nop 0
	v_pk_add_f32 v[100:101], v[100:101], v[80:81]
	v_pk_add_f32 v[100:101], v[100:101], v[96:97]
	v_add_f32_e32 v99, v100, v101
	s_mul_i32 s8, s48, 0x8c00
	v_fmac_f32_e32 v99, v193, v98
	v_add_u32_e32 v98, s8, v212
	v_cvt_pk_bf16_f32 v66, v66, v67
	v_cvt_pk_bf16_f32 v67, v68, v69
	v_cvt_pk_bf16_f32 v68, v70, v71
	v_cvt_pk_bf16_f32 v69, v72, v73
	v_cvt_pk_bf16_f32 v70, v74, v75
	v_cvt_pk_bf16_f32 v71, v76, v77
	v_cvt_pk_bf16_f32 v72, v78, v79
	v_cvt_pk_bf16_f32 v73, v80, v81
	v_cvt_pk_bf16_f32 v74, v82, v83
	v_cvt_pk_bf16_f32 v75, v84, v85
	v_cvt_pk_bf16_f32 v76, v86, v87
	v_cvt_pk_bf16_f32 v77, v88, v89
	v_cvt_pk_bf16_f32 v78, v90, v91
	v_cvt_pk_bf16_f32 v79, v92, v93
	v_cvt_pk_bf16_f32 v80, v94, v95
	v_cvt_pk_bf16_f32 v81, v96, v97
	ds_read_b128 v[82:85], v98 offset:17408
	ds_read_b128 v[86:89], v98 offset:22016
	ds_read_b128 v[90:93], v98 offset:26624
	ds_read_b128 v[94:97], v98 offset:31232
	s_setprio 1
	s_waitcnt lgkmcnt(3)
	v_mfma_f32_32x32x16_bf16 v[50:65], v[82:85], v[66:69], v[50:65]
	s_waitcnt lgkmcnt(2)
	v_mfma_f32_32x32x16_bf16 v[34:49], v[86:89], v[66:69], v[34:49]
	s_waitcnt lgkmcnt(1)
	v_mfma_f32_32x32x16_bf16 v[18:33], v[90:93], v[66:69], v[18:33]
	s_waitcnt lgkmcnt(0)
	v_mfma_f32_32x32x16_bf16 v[2:17], v[94:97], v[66:69], v[2:17]
	s_setprio 0
	ds_read_b128 v[66:69], v98 offset:17440
	ds_read_b128 v[82:85], v98 offset:22048
	ds_read_b128 v[86:89], v98 offset:26656
	ds_read_b128 v[90:93], v98 offset:31264
	s_setprio 1
	s_waitcnt lgkmcnt(3)
	v_mfma_f32_32x32x16_bf16 v[50:65], v[66:69], v[70:73], v[50:65]
	s_waitcnt lgkmcnt(2)
	v_mfma_f32_32x32x16_bf16 v[34:49], v[82:85], v[70:73], v[34:49]
	s_waitcnt lgkmcnt(1)
	v_mfma_f32_32x32x16_bf16 v[18:33], v[86:89], v[70:73], v[18:33]
	s_waitcnt lgkmcnt(0)
	v_mfma_f32_32x32x16_bf16 v[2:17], v[90:93], v[70:73], v[2:17]
	s_setprio 0
	ds_read_b128 v[66:69], v98 offset:17472
	ds_read_b128 v[70:73], v98 offset:22080
	ds_read_b128 v[82:85], v98 offset:26688
	ds_read_b128 v[86:89], v98 offset:31296
	s_setprio 1
	s_waitcnt lgkmcnt(3)
	v_mfma_f32_32x32x16_bf16 v[50:65], v[66:69], v[74:77], v[50:65]
	s_waitcnt lgkmcnt(2)
	v_mfma_f32_32x32x16_bf16 v[34:49], v[70:73], v[74:77], v[34:49]
	s_waitcnt lgkmcnt(1)
	v_mfma_f32_32x32x16_bf16 v[18:33], v[82:85], v[74:77], v[18:33]
	s_waitcnt lgkmcnt(0)
	v_mfma_f32_32x32x16_bf16 v[2:17], v[86:89], v[74:77], v[2:17]
	s_setprio 0
	ds_read_b128 v[66:69], v98 offset:17504
	ds_read_b128 v[70:73], v98 offset:22112
	ds_read_b128 v[74:77], v98 offset:26720
	ds_read_b128 v[82:85], v98 offset:31328
	s_setprio 1
	s_waitcnt lgkmcnt(3)
	v_mfma_f32_32x32x16_bf16 v[50:65], v[66:69], v[78:81], v[50:65]
	s_waitcnt lgkmcnt(2)
	v_mfma_f32_32x32x16_bf16 v[34:49], v[70:73], v[78:81], v[34:49]
	s_waitcnt lgkmcnt(1)
	v_mfma_f32_32x32x16_bf16 v[18:33], v[74:77], v[78:81], v[18:33]
	s_waitcnt lgkmcnt(0)
	v_mfma_f32_32x32x16_bf16 v[2:17], v[82:85], v[78:81], v[2:17]
	s_setprio 0
	v_mov_b32_e32 v193, v99

.LBB0_70:
	v_pk_add_f32 v[66:67], v[66:67], v[202:203] op_sel:[0,1] op_sel_hi:[1,1] neg_lo:[0,1] neg_hi:[0,1]
	v_pk_add_f32 v[82:83], v[82:83], v[202:203] op_sel:[0,1] op_sel_hi:[1,1] neg_lo:[0,1] neg_hi:[0,1]
	v_exp_f32_e32 v66, v66
	v_exp_f32_e32 v67, v67
	v_exp_f32_e32 v82, v82
	v_exp_f32_e32 v83, v83
	v_pk_add_f32 v[68:69], v[68:69], v[202:203] op_sel:[0,1] op_sel_hi:[1,1] neg_lo:[0,1] neg_hi:[0,1]
	v_pk_add_f32 v[84:85], v[84:85], v[202:203] op_sel:[0,1] op_sel_hi:[1,1] neg_lo:[0,1] neg_hi:[0,1]
	v_exp_f32_e32 v68, v68
	v_exp_f32_e32 v69, v69
	v_exp_f32_e32 v84, v84
	v_exp_f32_e32 v85, v85
	v_pk_add_f32 v[174:175], v[66:67], v[82:83]
	v_pk_add_f32 v[70:71], v[70:71], v[202:203] op_sel:[0,1] op_sel_hi:[1,1] neg_lo:[0,1] neg_hi:[0,1]
	v_pk_add_f32 v[86:87], v[86:87], v[202:203] op_sel:[0,1] op_sel_hi:[1,1] neg_lo:[0,1] neg_hi:[0,1]
	v_exp_f32_e32 v70, v70
	v_exp_f32_e32 v71, v71
	v_exp_f32_e32 v86, v86
	v_exp_f32_e32 v87, v87
	v_pk_add_f32 v[174:175], v[174:175], v[68:69]
	v_pk_add_f32 v[174:175], v[174:175], v[84:85]
	v_pk_add_f32 v[72:73], v[72:73], v[202:203] op_sel:[0,1] op_sel_hi:[1,1] neg_lo:[0,1] neg_hi:[0,1]
	v_pk_add_f32 v[88:89], v[88:89], v[202:203] op_sel:[0,1] op_sel_hi:[1,1] neg_lo:[0,1] neg_hi:[0,1]
	v_exp_f32_e32 v72, v72
	v_exp_f32_e32 v73, v73
	v_exp_f32_e32 v88, v88
	v_exp_f32_e32 v89, v89
	v_pk_add_f32 v[174:175], v[174:175], v[70:71]
	v_pk_add_f32 v[174:175], v[174:175], v[86:87]
	v_pk_add_f32 v[74:75], v[74:75], v[202:203] op_sel:[0,1] op_sel_hi:[1,1] neg_lo:[0,1] neg_hi:[0,1]
	v_pk_add_f32 v[90:91], v[90:91], v[202:203] op_sel:[0,1] op_sel_hi:[1,1] neg_lo:[0,1] neg_hi:[0,1]
	v_exp_f32_e32 v74, v74
	v_exp_f32_e32 v75, v75
	v_exp_f32_e32 v90, v90
	v_exp_f32_e32 v91, v91
	v_pk_add_f32 v[174:175], v[174:175], v[72:73]
	v_pk_add_f32 v[174:175], v[174:175], v[88:89]
	v_pk_add_f32 v[76:77], v[76:77], v[202:203] op_sel:[0,1] op_sel_hi:[1,1] neg_lo:[0,1] neg_hi:[0,1]
	v_pk_add_f32 v[92:93], v[92:93], v[202:203] op_sel:[0,1] op_sel_hi:[1,1] neg_lo:[0,1] neg_hi:[0,1]
	v_exp_f32_e32 v76, v76
	v_exp_f32_e32 v77, v77
	v_exp_f32_e32 v92, v92
	v_exp_f32_e32 v93, v93
	v_pk_add_f32 v[174:175], v[174:175], v[74:75]
	v_pk_add_f32 v[174:175], v[174:175], v[90:91]
	v_pk_add_f32 v[78:79], v[78:79], v[202:203] op_sel:[0,1] op_sel_hi:[1,1] neg_lo:[0,1] neg_hi:[0,1]
	v_pk_add_f32 v[94:95], v[94:95], v[202:203] op_sel:[0,1] op_sel_hi:[1,1] neg_lo:[0,1] neg_hi:[0,1]
	v_exp_f32_e32 v78, v78
	v_exp_f32_e32 v79, v79
	v_exp_f32_e32 v94, v94
	v_exp_f32_e32 v95, v95
	v_pk_add_f32 v[174:175], v[174:175], v[76:77]
	v_pk_add_f32 v[174:175], v[174:175], v[92:93]
	v_pk_add_f32 v[80:81], v[80:81], v[202:203] op_sel:[0,1] op_sel_hi:[1,1] neg_lo:[0,1] neg_hi:[0,1]
	v_pk_add_f32 v[96:97], v[96:97], v[202:203] op_sel:[0,1] op_sel_hi:[1,1] neg_lo:[0,1] neg_hi:[0,1]
	v_exp_f32_e32 v80, v80
	v_exp_f32_e32 v81, v81
	v_exp_f32_e32 v96, v96
	v_exp_f32_e32 v97, v97
	v_pk_add_f32 v[174:175], v[174:175], v[78:79]
	v_pk_add_f32 v[174:175], v[174:175], v[94:95]
	s_nop 0
	v_pk_add_f32 v[174:175], v[174:175], v[80:81]
	v_pk_add_f32 v[174:175], v[174:175], v[96:97]
	v_add_f32_e32 v216, v174, v175
	v_fmac_f32_e32 v216, v193, v202
	v_add3_u32 v193, s47, v210, v211
	v_cvt_pk_bf16_f32 v174, v66, v67
	v_cvt_pk_bf16_f32 v175, v68, v69
	v_cvt_pk_bf16_f32 v176, v70, v71
	v_cvt_pk_bf16_f32 v177, v72, v73
	v_cvt_pk_bf16_f32 v218, v74, v75
	v_cvt_pk_bf16_f32 v219, v76, v77
	v_cvt_pk_bf16_f32 v220, v78, v79
	v_cvt_pk_bf16_f32 v221, v80, v81
	v_cvt_pk_bf16_f32 v222, v82, v83
	v_cvt_pk_bf16_f32 v223, v84, v85
	v_cvt_pk_bf16_f32 v224, v86, v87
	v_cvt_pk_bf16_f32 v225, v88, v89
	v_cvt_pk_bf16_f32 v226, v90, v91
	v_cvt_pk_bf16_f32 v227, v92, v93
	v_cvt_pk_bf16_f32 v228, v94, v95
	v_cvt_pk_bf16_f32 v229, v96, v97
	ds_read_b128 v[232:235], v193 offset:17408
	ds_read_b128 v[236:239], v193 offset:22016
	ds_read_b128 v[240:243], v193 offset:26624
	ds_read_b128 v[248:251], v193 offset:31232
	s_setprio 1
	s_waitcnt lgkmcnt(3)
	v_mfma_f32_32x32x16_bf16 v[50:65], v[232:235], v[174:177], v[50:65]
	s_waitcnt lgkmcnt(2)
	v_mfma_f32_32x32x16_bf16 v[34:49], v[236:239], v[174:177], v[34:49]
	s_waitcnt lgkmcnt(1)
	v_mfma_f32_32x32x16_bf16 v[18:33], v[240:243], v[174:177], v[18:33]
	s_waitcnt lgkmcnt(0)
	v_mfma_f32_32x32x16_bf16 v[2:17], v[248:251], v[174:177], v[2:17]
	s_setprio 0
	ds_read_b128 v[174:177], v193 offset:17440
	ds_read_b128 v[232:235], v193 offset:22048
	ds_read_b128 v[236:239], v193 offset:26656
	ds_read_b128 v[240:243], v193 offset:31264
	s_setprio 1
	s_waitcnt lgkmcnt(3)
	v_mfma_f32_32x32x16_bf16 v[50:65], v[174:177], v[218:221], v[50:65]
	s_waitcnt lgkmcnt(2)
	v_mfma_f32_32x32x16_bf16 v[34:49], v[232:235], v[218:221], v[34:49]
	s_waitcnt lgkmcnt(1)
	v_mfma_f32_32x32x16_bf16 v[18:33], v[236:239], v[218:221], v[18:33]
	s_waitcnt lgkmcnt(0)
	v_mfma_f32_32x32x16_bf16 v[2:17], v[240:243], v[218:221], v[2:17]
	s_setprio 0
	ds_read_b128 v[174:177], v193 offset:17472
	ds_read_b128 v[218:221], v193 offset:22080
	ds_read_b128 v[232:235], v193 offset:26688
	ds_read_b128 v[236:239], v193 offset:31296
	s_setprio 1
	s_waitcnt lgkmcnt(3)
	v_mfma_f32_32x32x16_bf16 v[50:65], v[174:177], v[222:225], v[50:65]
	s_waitcnt lgkmcnt(2)
	v_mfma_f32_32x32x16_bf16 v[34:49], v[218:221], v[222:225], v[34:49]
	s_waitcnt lgkmcnt(1)
	v_mfma_f32_32x32x16_bf16 v[18:33], v[232:235], v[222:225], v[18:33]
	s_waitcnt lgkmcnt(0)
	v_mfma_f32_32x32x16_bf16 v[2:17], v[236:239], v[222:225], v[2:17]
	s_setprio 0
	ds_read_b128 v[174:177], v193 offset:17504
	ds_read_b128 v[218:221], v193 offset:22112
	ds_read_b128 v[222:225], v193 offset:26720
	ds_read_b128 v[232:235], v193 offset:31328
	s_setprio 1
	s_waitcnt lgkmcnt(3)
	v_mfma_f32_32x32x16_bf16 v[50:65], v[174:177], v[226:229], v[50:65]
	s_waitcnt lgkmcnt(2)
	v_mfma_f32_32x32x16_bf16 v[34:49], v[218:221], v[226:229], v[34:49]
	s_waitcnt lgkmcnt(1)
	v_mfma_f32_32x32x16_bf16 v[18:33], v[222:225], v[226:229], v[18:33]
	s_waitcnt lgkmcnt(0)
	v_mfma_f32_32x32x16_bf16 v[2:17], v[232:235], v[226:229], v[2:17]
	s_setprio 0

.LBB0_75:
	v_pk_add_f32 v[66:67], v[66:67], v[216:217] op_sel_hi:[1,0] neg_lo:[0,1] neg_hi:[0,1]
	v_pk_add_f32 v[82:83], v[82:83], v[216:217] op_sel_hi:[1,0] neg_lo:[0,1] neg_hi:[0,1]
	v_exp_f32_e32 v66, v66
	v_exp_f32_e32 v67, v67
	v_exp_f32_e32 v82, v82
	v_exp_f32_e32 v83, v83
	v_pk_add_f32 v[68:69], v[68:69], v[216:217] op_sel_hi:[1,0] neg_lo:[0,1] neg_hi:[0,1]
	v_pk_add_f32 v[84:85], v[84:85], v[216:217] op_sel_hi:[1,0] neg_lo:[0,1] neg_hi:[0,1]
	v_exp_f32_e32 v68, v68
	v_exp_f32_e32 v69, v69
	v_exp_f32_e32 v84, v84
	v_exp_f32_e32 v85, v85
	v_pk_add_f32 v[174:175], v[66:67], v[82:83]
	v_pk_add_f32 v[70:71], v[70:71], v[216:217] op_sel_hi:[1,0] neg_lo:[0,1] neg_hi:[0,1]
	v_pk_add_f32 v[86:87], v[86:87], v[216:217] op_sel_hi:[1,0] neg_lo:[0,1] neg_hi:[0,1]
	v_exp_f32_e32 v70, v70
	v_exp_f32_e32 v71, v71
	v_exp_f32_e32 v86, v86
	v_exp_f32_e32 v87, v87
	v_pk_add_f32 v[174:175], v[174:175], v[68:69]
	v_pk_add_f32 v[174:175], v[174:175], v[84:85]
	v_pk_add_f32 v[72:73], v[72:73], v[216:217] op_sel_hi:[1,0] neg_lo:[0,1] neg_hi:[0,1]
	v_pk_add_f32 v[88:89], v[88:89], v[216:217] op_sel_hi:[1,0] neg_lo:[0,1] neg_hi:[0,1]
	v_exp_f32_e32 v72, v72
	v_exp_f32_e32 v73, v73
	v_exp_f32_e32 v88, v88
	v_exp_f32_e32 v89, v89
	v_pk_add_f32 v[174:175], v[174:175], v[70:71]
	v_pk_add_f32 v[174:175], v[174:175], v[86:87]
	v_pk_add_f32 v[74:75], v[74:75], v[216:217] op_sel_hi:[1,0] neg_lo:[0,1] neg_hi:[0,1]
	v_pk_add_f32 v[90:91], v[90:91], v[216:217] op_sel_hi:[1,0] neg_lo:[0,1] neg_hi:[0,1]
	v_exp_f32_e32 v74, v74
	v_exp_f32_e32 v75, v75
	v_exp_f32_e32 v90, v90
	v_exp_f32_e32 v91, v91
	v_pk_add_f32 v[174:175], v[174:175], v[72:73]
	v_pk_add_f32 v[174:175], v[174:175], v[88:89]
	v_pk_add_f32 v[76:77], v[76:77], v[216:217] op_sel_hi:[1,0] neg_lo:[0,1] neg_hi:[0,1]
	v_pk_add_f32 v[92:93], v[92:93], v[216:217] op_sel_hi:[1,0] neg_lo:[0,1] neg_hi:[0,1]
	v_exp_f32_e32 v76, v76
	v_exp_f32_e32 v77, v77
	v_exp_f32_e32 v92, v92
	v_exp_f32_e32 v93, v93
	v_pk_add_f32 v[174:175], v[174:175], v[74:75]
	v_pk_add_f32 v[174:175], v[174:175], v[90:91]
	v_pk_add_f32 v[78:79], v[78:79], v[216:217] op_sel_hi:[1,0] neg_lo:[0,1] neg_hi:[0,1]
	v_pk_add_f32 v[94:95], v[94:95], v[216:217] op_sel_hi:[1,0] neg_lo:[0,1] neg_hi:[0,1]
	v_exp_f32_e32 v78, v78
	v_exp_f32_e32 v79, v79
	v_exp_f32_e32 v94, v94
	v_exp_f32_e32 v95, v95
	v_pk_add_f32 v[174:175], v[174:175], v[76:77]
	v_pk_add_f32 v[174:175], v[174:175], v[92:93]
	v_pk_add_f32 v[80:81], v[80:81], v[216:217] op_sel_hi:[1,0] neg_lo:[0,1] neg_hi:[0,1]
	v_pk_add_f32 v[96:97], v[96:97], v[216:217] op_sel_hi:[1,0] neg_lo:[0,1] neg_hi:[0,1]
	v_exp_f32_e32 v80, v80
	v_exp_f32_e32 v81, v81
	v_exp_f32_e32 v96, v96
	v_exp_f32_e32 v97, v97
	v_pk_add_f32 v[174:175], v[174:175], v[78:79]
	v_pk_add_f32 v[174:175], v[174:175], v[94:95]
	s_mul_i32 s48, s48, 0x8c00
	s_nop 0
	v_pk_add_f32 v[174:175], v[174:175], v[80:81]
	v_pk_add_f32 v[174:175], v[174:175], v[96:97]
	v_add_f32_e32 v216, v174, v175
	v_add_u32_e32 v174, s48, v212
	v_cvt_pk_bf16_f32 v66, v66, v67
	v_cvt_pk_bf16_f32 v67, v68, v69
	v_cvt_pk_bf16_f32 v68, v70, v71
	v_cvt_pk_bf16_f32 v69, v72, v73
	v_cvt_pk_bf16_f32 v70, v74, v75
	v_cvt_pk_bf16_f32 v71, v76, v77
	v_cvt_pk_bf16_f32 v72, v78, v79
	v_cvt_pk_bf16_f32 v73, v80, v81
	v_cvt_pk_bf16_f32 v74, v82, v83
	v_cvt_pk_bf16_f32 v75, v84, v85
	v_cvt_pk_bf16_f32 v76, v86, v87
	v_cvt_pk_bf16_f32 v77, v88, v89
	v_cvt_pk_bf16_f32 v78, v90, v91
	v_cvt_pk_bf16_f32 v79, v92, v93
	v_cvt_pk_bf16_f32 v80, v94, v95
	v_cvt_pk_bf16_f32 v81, v96, v97
	ds_read_b128 v[82:85], v174 offset:17408
	ds_read_b128 v[86:89], v174 offset:22016
	ds_read_b128 v[90:93], v174 offset:26624
	ds_read_b128 v[94:97], v174 offset:31232
	v_fmac_f32_e32 v216, v193, v202
	s_setprio 1
	s_waitcnt lgkmcnt(3)
	v_mfma_f32_32x32x16_bf16 v[50:65], v[82:85], v[66:69], v[50:65]
	s_waitcnt lgkmcnt(2)
	v_mfma_f32_32x32x16_bf16 v[34:49], v[86:89], v[66:69], v[34:49]
	s_waitcnt lgkmcnt(1)
	v_mfma_f32_32x32x16_bf16 v[18:33], v[90:93], v[66:69], v[18:33]
	s_waitcnt lgkmcnt(0)
	v_mfma_f32_32x32x16_bf16 v[2:17], v[94:97], v[66:69], v[2:17]
	s_setprio 0
	ds_read_b128 v[66:69], v174 offset:17440
	ds_read_b128 v[82:85], v174 offset:22048
	ds_read_b128 v[86:89], v174 offset:26656
	ds_read_b128 v[90:93], v174 offset:31264
	s_setprio 1
	s_waitcnt lgkmcnt(3)
	v_mfma_f32_32x32x16_bf16 v[50:65], v[66:69], v[70:73], v[50:65]
	s_waitcnt lgkmcnt(2)
	v_mfma_f32_32x32x16_bf16 v[34:49], v[82:85], v[70:73], v[34:49]
	s_waitcnt lgkmcnt(1)
	v_mfma_f32_32x32x16_bf16 v[18:33], v[86:89], v[70:73], v[18:33]
	s_waitcnt lgkmcnt(0)
	v_mfma_f32_32x32x16_bf16 v[2:17], v[90:93], v[70:73], v[2:17]
	s_setprio 0
	ds_read_b128 v[66:69], v174 offset:17472
	ds_read_b128 v[70:73], v174 offset:22080
	ds_read_b128 v[82:85], v174 offset:26688
	ds_read_b128 v[86:89], v174 offset:31296
	s_setprio 1
	s_waitcnt lgkmcnt(3)
	v_mfma_f32_32x32x16_bf16 v[50:65], v[66:69], v[74:77], v[50:65]
	s_waitcnt lgkmcnt(2)
	v_mfma_f32_32x32x16_bf16 v[34:49], v[70:73], v[74:77], v[34:49]
	s_waitcnt lgkmcnt(1)
	v_mfma_f32_32x32x16_bf16 v[18:33], v[82:85], v[74:77], v[18:33]
	s_waitcnt lgkmcnt(0)
	v_mfma_f32_32x32x16_bf16 v[2:17], v[86:89], v[74:77], v[2:17]
	s_setprio 0
	ds_read_b128 v[66:69], v174 offset:17504
	ds_read_b128 v[70:73], v174 offset:22112
	ds_read_b128 v[74:77], v174 offset:26720
	ds_read_b128 v[82:85], v174 offset:31328
	s_setprio 1
	s_waitcnt lgkmcnt(3)
	v_mfma_f32_32x32x16_bf16 v[50:65], v[66:69], v[78:81], v[50:65]
	s_waitcnt lgkmcnt(2)
	v_mfma_f32_32x32x16_bf16 v[34:49], v[70:73], v[78:81], v[34:49]
	s_waitcnt lgkmcnt(1)
	v_mfma_f32_32x32x16_bf16 v[18:33], v[74:77], v[78:81], v[18:33]
	s_waitcnt lgkmcnt(0)
	v_mfma_f32_32x32x16_bf16 v[2:17], v[82:85], v[78:81], v[2:17]
	s_setprio 0
	s_branch .LBB0_77

.LBB0_92:
	v_pk_add_f32 v[66:67], v[66:67], v[192:193] op_sel:[0,1] op_sel_hi:[1,1] neg_lo:[0,1] neg_hi:[0,1]
	v_pk_add_f32 v[82:83], v[82:83], v[192:193] op_sel:[0,1] op_sel_hi:[1,1] neg_lo:[0,1] neg_hi:[0,1]
	v_exp_f32_e32 v66, v66
	v_exp_f32_e32 v67, v67
	v_exp_f32_e32 v82, v82
	v_exp_f32_e32 v83, v83
	v_pk_add_f32 v[68:69], v[68:69], v[192:193] op_sel:[0,1] op_sel_hi:[1,1] neg_lo:[0,1] neg_hi:[0,1]
	v_pk_add_f32 v[84:85], v[84:85], v[192:193] op_sel:[0,1] op_sel_hi:[1,1] neg_lo:[0,1] neg_hi:[0,1]
	v_exp_f32_e32 v68, v68
	v_exp_f32_e32 v69, v69
	v_exp_f32_e32 v84, v84
	v_exp_f32_e32 v85, v85
	v_pk_add_f32 v[174:175], v[66:67], v[82:83]
	v_pk_add_f32 v[70:71], v[70:71], v[192:193] op_sel:[0,1] op_sel_hi:[1,1] neg_lo:[0,1] neg_hi:[0,1]
	v_pk_add_f32 v[86:87], v[86:87], v[192:193] op_sel:[0,1] op_sel_hi:[1,1] neg_lo:[0,1] neg_hi:[0,1]
	v_exp_f32_e32 v70, v70
	v_exp_f32_e32 v71, v71
	v_exp_f32_e32 v86, v86
	v_exp_f32_e32 v87, v87
	v_pk_add_f32 v[174:175], v[174:175], v[68:69]
	v_pk_add_f32 v[174:175], v[174:175], v[84:85]
	v_pk_add_f32 v[72:73], v[72:73], v[192:193] op_sel:[0,1] op_sel_hi:[1,1] neg_lo:[0,1] neg_hi:[0,1]
	v_pk_add_f32 v[88:89], v[88:89], v[192:193] op_sel:[0,1] op_sel_hi:[1,1] neg_lo:[0,1] neg_hi:[0,1]
	v_exp_f32_e32 v72, v72
	v_exp_f32_e32 v73, v73
	v_exp_f32_e32 v88, v88
	v_exp_f32_e32 v89, v89
	v_pk_add_f32 v[174:175], v[174:175], v[70:71]
	v_pk_add_f32 v[174:175], v[174:175], v[86:87]
	v_pk_add_f32 v[74:75], v[74:75], v[192:193] op_sel:[0,1] op_sel_hi:[1,1] neg_lo:[0,1] neg_hi:[0,1]
	v_pk_add_f32 v[90:91], v[90:91], v[192:193] op_sel:[0,1] op_sel_hi:[1,1] neg_lo:[0,1] neg_hi:[0,1]
	v_exp_f32_e32 v74, v74
	v_exp_f32_e32 v75, v75
	v_exp_f32_e32 v90, v90
	v_exp_f32_e32 v91, v91
	v_pk_add_f32 v[174:175], v[174:175], v[72:73]
	v_pk_add_f32 v[174:175], v[174:175], v[88:89]
	v_pk_add_f32 v[76:77], v[76:77], v[192:193] op_sel:[0,1] op_sel_hi:[1,1] neg_lo:[0,1] neg_hi:[0,1]
	v_pk_add_f32 v[92:93], v[92:93], v[192:193] op_sel:[0,1] op_sel_hi:[1,1] neg_lo:[0,1] neg_hi:[0,1]
	v_exp_f32_e32 v76, v76
	v_exp_f32_e32 v77, v77
	v_exp_f32_e32 v92, v92
	v_exp_f32_e32 v93, v93
	v_pk_add_f32 v[174:175], v[174:175], v[74:75]
	v_pk_add_f32 v[174:175], v[174:175], v[90:91]
	v_pk_add_f32 v[78:79], v[78:79], v[192:193] op_sel:[0,1] op_sel_hi:[1,1] neg_lo:[0,1] neg_hi:[0,1]
	v_pk_add_f32 v[94:95], v[94:95], v[192:193] op_sel:[0,1] op_sel_hi:[1,1] neg_lo:[0,1] neg_hi:[0,1]
	v_exp_f32_e32 v78, v78
	v_exp_f32_e32 v79, v79
	v_exp_f32_e32 v94, v94
	v_exp_f32_e32 v95, v95
	v_pk_add_f32 v[174:175], v[174:175], v[76:77]
	v_pk_add_f32 v[174:175], v[174:175], v[92:93]
	v_pk_add_f32 v[80:81], v[80:81], v[192:193] op_sel:[0,1] op_sel_hi:[1,1] neg_lo:[0,1] neg_hi:[0,1]
	v_pk_add_f32 v[96:97], v[96:97], v[192:193] op_sel:[0,1] op_sel_hi:[1,1] neg_lo:[0,1] neg_hi:[0,1]
	v_exp_f32_e32 v80, v80
	v_exp_f32_e32 v81, v81
	v_exp_f32_e32 v96, v96
	v_exp_f32_e32 v97, v97
	v_pk_add_f32 v[174:175], v[174:175], v[78:79]
	v_pk_add_f32 v[174:175], v[174:175], v[94:95]
	s_nop 0
	v_pk_add_f32 v[174:175], v[174:175], v[80:81]
	v_pk_add_f32 v[174:175], v[174:175], v[96:97]
	v_add_f32_e32 v193, v174, v175
	v_fmac_f32_e32 v193, v216, v204
	v_add3_u32 v204, s30, v210, v211
	v_cvt_pk_bf16_f32 v174, v66, v67
	v_cvt_pk_bf16_f32 v175, v68, v69
	v_cvt_pk_bf16_f32 v176, v70, v71
	v_cvt_pk_bf16_f32 v177, v72, v73
	v_cvt_pk_bf16_f32 v216, v74, v75
	v_cvt_pk_bf16_f32 v217, v76, v77
	v_cvt_pk_bf16_f32 v218, v78, v79
	v_cvt_pk_bf16_f32 v219, v80, v81
	v_cvt_pk_bf16_f32 v220, v82, v83
	v_cvt_pk_bf16_f32 v221, v84, v85
	v_cvt_pk_bf16_f32 v222, v86, v87
	v_cvt_pk_bf16_f32 v223, v88, v89
	v_cvt_pk_bf16_f32 v224, v90, v91
	v_cvt_pk_bf16_f32 v225, v92, v93
	v_cvt_pk_bf16_f32 v226, v94, v95
	v_cvt_pk_bf16_f32 v227, v96, v97
	ds_read_b128 v[232:235], v204 offset:17408
	ds_read_b128 v[236:239], v204 offset:22016
	ds_read_b128 v[240:243], v204 offset:26624
	ds_read_b128 v[248:251], v204 offset:31232
	s_setprio 1
	s_waitcnt lgkmcnt(3)
	v_mfma_f32_32x32x16_bf16 v[50:65], v[232:235], v[174:177], v[50:65]
	s_waitcnt lgkmcnt(2)
	v_mfma_f32_32x32x16_bf16 v[34:49], v[236:239], v[174:177], v[34:49]
	s_waitcnt lgkmcnt(1)
	v_mfma_f32_32x32x16_bf16 v[18:33], v[240:243], v[174:177], v[18:33]
	s_waitcnt lgkmcnt(0)
	v_mfma_f32_32x32x16_bf16 v[2:17], v[248:251], v[174:177], v[2:17]
	s_setprio 0
	ds_read_b128 v[174:177], v204 offset:17440
	ds_read_b128 v[232:235], v204 offset:22048
	ds_read_b128 v[236:239], v204 offset:26656
	ds_read_b128 v[240:243], v204 offset:31264
	s_setprio 1
	s_waitcnt lgkmcnt(3)
	v_mfma_f32_32x32x16_bf16 v[50:65], v[174:177], v[216:219], v[50:65]
	s_waitcnt lgkmcnt(2)
	v_mfma_f32_32x32x16_bf16 v[34:49], v[232:235], v[216:219], v[34:49]
	s_waitcnt lgkmcnt(1)
	v_mfma_f32_32x32x16_bf16 v[18:33], v[236:239], v[216:219], v[18:33]
	s_waitcnt lgkmcnt(0)
	v_mfma_f32_32x32x16_bf16 v[2:17], v[240:243], v[216:219], v[2:17]
	s_setprio 0
	ds_read_b128 v[174:177], v204 offset:17472
	ds_read_b128 v[216:219], v204 offset:22080
	ds_read_b128 v[232:235], v204 offset:26688
	ds_read_b128 v[236:239], v204 offset:31296
	s_setprio 1
	s_waitcnt lgkmcnt(3)
	v_mfma_f32_32x32x16_bf16 v[50:65], v[174:177], v[220:223], v[50:65]
	s_waitcnt lgkmcnt(2)
	v_mfma_f32_32x32x16_bf16 v[34:49], v[216:219], v[220:223], v[34:49]
	s_waitcnt lgkmcnt(1)
	v_mfma_f32_32x32x16_bf16 v[18:33], v[232:235], v[220:223], v[18:33]
	s_waitcnt lgkmcnt(0)
	v_mfma_f32_32x32x16_bf16 v[2:17], v[236:239], v[220:223], v[2:17]
	s_setprio 0
	ds_read_b128 v[174:177], v204 offset:17504
	ds_read_b128 v[216:219], v204 offset:22112
	ds_read_b128 v[220:223], v204 offset:26720
	ds_read_b128 v[232:235], v204 offset:31328
	s_setprio 1
	s_waitcnt lgkmcnt(3)
	v_mfma_f32_32x32x16_bf16 v[50:65], v[174:177], v[224:227], v[50:65]
	s_waitcnt lgkmcnt(2)
	v_mfma_f32_32x32x16_bf16 v[34:49], v[216:219], v[224:227], v[34:49]
	s_waitcnt lgkmcnt(1)
	v_mfma_f32_32x32x16_bf16 v[18:33], v[220:223], v[224:227], v[18:33]
	s_waitcnt lgkmcnt(0)
	v_mfma_f32_32x32x16_bf16 v[2:17], v[232:235], v[224:227], v[2:17]
	s_setprio 0
	s_andn2_saveexec_b64 s[0:1], s[0:1]
	s_cbranch_execz .LBB0_87

.LBB0_95:
	v_pk_add_f32 v[66:67], v[66:67], v[192:193] op_sel:[0,1] op_sel_hi:[1,1] neg_lo:[0,1] neg_hi:[0,1]
	v_pk_add_f32 v[82:83], v[82:83], v[192:193] op_sel:[0,1] op_sel_hi:[1,1] neg_lo:[0,1] neg_hi:[0,1]
	v_exp_f32_e32 v66, v66
	v_exp_f32_e32 v67, v67
	v_exp_f32_e32 v82, v82
	v_exp_f32_e32 v83, v83
	v_pk_add_f32 v[68:69], v[68:69], v[192:193] op_sel:[0,1] op_sel_hi:[1,1] neg_lo:[0,1] neg_hi:[0,1]
	v_pk_add_f32 v[84:85], v[84:85], v[192:193] op_sel:[0,1] op_sel_hi:[1,1] neg_lo:[0,1] neg_hi:[0,1]
	v_exp_f32_e32 v68, v68
	v_exp_f32_e32 v69, v69
	v_exp_f32_e32 v84, v84
	v_exp_f32_e32 v85, v85
	v_pk_add_f32 v[174:175], v[66:67], v[82:83]
	v_pk_add_f32 v[70:71], v[70:71], v[192:193] op_sel:[0,1] op_sel_hi:[1,1] neg_lo:[0,1] neg_hi:[0,1]
	v_pk_add_f32 v[86:87], v[86:87], v[192:193] op_sel:[0,1] op_sel_hi:[1,1] neg_lo:[0,1] neg_hi:[0,1]
	v_exp_f32_e32 v70, v70
	v_exp_f32_e32 v71, v71
	v_exp_f32_e32 v86, v86
	v_exp_f32_e32 v87, v87
	v_pk_add_f32 v[174:175], v[174:175], v[68:69]
	v_pk_add_f32 v[174:175], v[174:175], v[84:85]
	v_pk_add_f32 v[72:73], v[72:73], v[192:193] op_sel:[0,1] op_sel_hi:[1,1] neg_lo:[0,1] neg_hi:[0,1]
	v_pk_add_f32 v[88:89], v[88:89], v[192:193] op_sel:[0,1] op_sel_hi:[1,1] neg_lo:[0,1] neg_hi:[0,1]
	v_exp_f32_e32 v72, v72
	v_exp_f32_e32 v73, v73
	v_exp_f32_e32 v88, v88
	v_exp_f32_e32 v89, v89
	v_pk_add_f32 v[174:175], v[174:175], v[70:71]
	v_pk_add_f32 v[174:175], v[174:175], v[86:87]
	v_pk_add_f32 v[74:75], v[74:75], v[192:193] op_sel:[0,1] op_sel_hi:[1,1] neg_lo:[0,1] neg_hi:[0,1]
	v_pk_add_f32 v[90:91], v[90:91], v[192:193] op_sel:[0,1] op_sel_hi:[1,1] neg_lo:[0,1] neg_hi:[0,1]
	v_exp_f32_e32 v74, v74
	v_exp_f32_e32 v75, v75
	v_exp_f32_e32 v90, v90
	v_exp_f32_e32 v91, v91
	v_pk_add_f32 v[174:175], v[174:175], v[72:73]
	v_pk_add_f32 v[174:175], v[174:175], v[88:89]
	v_pk_add_f32 v[76:77], v[76:77], v[192:193] op_sel:[0,1] op_sel_hi:[1,1] neg_lo:[0,1] neg_hi:[0,1]
	v_pk_add_f32 v[92:93], v[92:93], v[192:193] op_sel:[0,1] op_sel_hi:[1,1] neg_lo:[0,1] neg_hi:[0,1]
	v_exp_f32_e32 v76, v76
	v_exp_f32_e32 v77, v77
	v_exp_f32_e32 v92, v92
	v_exp_f32_e32 v93, v93
	v_pk_add_f32 v[174:175], v[174:175], v[74:75]
	v_pk_add_f32 v[174:175], v[174:175], v[90:91]
	v_pk_add_f32 v[78:79], v[78:79], v[192:193] op_sel:[0,1] op_sel_hi:[1,1] neg_lo:[0,1] neg_hi:[0,1]
	v_pk_add_f32 v[94:95], v[94:95], v[192:193] op_sel:[0,1] op_sel_hi:[1,1] neg_lo:[0,1] neg_hi:[0,1]
	v_exp_f32_e32 v78, v78
	v_exp_f32_e32 v79, v79
	v_exp_f32_e32 v94, v94
	v_exp_f32_e32 v95, v95
	v_pk_add_f32 v[174:175], v[174:175], v[76:77]
	v_pk_add_f32 v[174:175], v[174:175], v[92:93]
	v_pk_add_f32 v[80:81], v[80:81], v[192:193] op_sel:[0,1] op_sel_hi:[1,1] neg_lo:[0,1] neg_hi:[0,1]
	v_pk_add_f32 v[96:97], v[96:97], v[192:193] op_sel:[0,1] op_sel_hi:[1,1] neg_lo:[0,1] neg_hi:[0,1]
	v_exp_f32_e32 v80, v80
	v_exp_f32_e32 v81, v81
	v_exp_f32_e32 v96, v96
	v_exp_f32_e32 v97, v97
	v_pk_add_f32 v[174:175], v[174:175], v[78:79]
	v_pk_add_f32 v[174:175], v[174:175], v[94:95]
	s_nop 0
	v_pk_add_f32 v[174:175], v[174:175], v[80:81]
	v_pk_add_f32 v[174:175], v[174:175], v[96:97]
	v_add_f32_e32 v193, v174, v175
	v_add3_u32 v174, s47, v210, v211
	v_cvt_pk_bf16_f32 v66, v66, v67
	v_cvt_pk_bf16_f32 v67, v68, v69
	v_cvt_pk_bf16_f32 v68, v70, v71
	v_cvt_pk_bf16_f32 v69, v72, v73
	v_cvt_pk_bf16_f32 v70, v74, v75
	v_cvt_pk_bf16_f32 v71, v76, v77
	v_cvt_pk_bf16_f32 v72, v78, v79
	v_cvt_pk_bf16_f32 v73, v80, v81
	v_cvt_pk_bf16_f32 v74, v82, v83
	v_cvt_pk_bf16_f32 v75, v84, v85
	v_cvt_pk_bf16_f32 v76, v86, v87
	v_cvt_pk_bf16_f32 v77, v88, v89
	v_cvt_pk_bf16_f32 v78, v90, v91
	v_cvt_pk_bf16_f32 v79, v92, v93
	v_cvt_pk_bf16_f32 v80, v94, v95
	v_cvt_pk_bf16_f32 v81, v96, v97
	ds_read_b128 v[82:85], v174 offset:17408
	ds_read_b128 v[86:89], v174 offset:22016
	ds_read_b128 v[90:93], v174 offset:26624
	ds_read_b128 v[94:97], v174 offset:31232
	v_fmac_f32_e32 v193, v216, v204
	s_setprio 1
	s_waitcnt lgkmcnt(3)
	v_mfma_f32_32x32x16_bf16 v[50:65], v[82:85], v[66:69], v[50:65]
	s_waitcnt lgkmcnt(2)
	v_mfma_f32_32x32x16_bf16 v[34:49], v[86:89], v[66:69], v[34:49]
	s_waitcnt lgkmcnt(1)
	v_mfma_f32_32x32x16_bf16 v[18:33], v[90:93], v[66:69], v[18:33]
	s_waitcnt lgkmcnt(0)
	v_mfma_f32_32x32x16_bf16 v[2:17], v[94:97], v[66:69], v[2:17]
	s_setprio 0
	ds_read_b128 v[66:69], v174 offset:17440
	ds_read_b128 v[82:85], v174 offset:22048
	ds_read_b128 v[86:89], v174 offset:26656
	ds_read_b128 v[90:93], v174 offset:31264
	s_setprio 1
	s_waitcnt lgkmcnt(3)
	v_mfma_f32_32x32x16_bf16 v[50:65], v[66:69], v[70:73], v[50:65]
	s_waitcnt lgkmcnt(2)
	v_mfma_f32_32x32x16_bf16 v[34:49], v[82:85], v[70:73], v[34:49]
	s_waitcnt lgkmcnt(1)
	v_mfma_f32_32x32x16_bf16 v[18:33], v[86:89], v[70:73], v[18:33]
	s_waitcnt lgkmcnt(0)
	v_mfma_f32_32x32x16_bf16 v[2:17], v[90:93], v[70:73], v[2:17]
	s_setprio 0
	ds_read_b128 v[66:69], v174 offset:17472
	ds_read_b128 v[70:73], v174 offset:22080
	ds_read_b128 v[82:85], v174 offset:26688
	ds_read_b128 v[86:89], v174 offset:31296
	s_setprio 1
	s_waitcnt lgkmcnt(3)
	v_mfma_f32_32x32x16_bf16 v[50:65], v[66:69], v[74:77], v[50:65]
	s_waitcnt lgkmcnt(2)
	v_mfma_f32_32x32x16_bf16 v[34:49], v[70:73], v[74:77], v[34:49]
	s_waitcnt lgkmcnt(1)
	v_mfma_f32_32x32x16_bf16 v[18:33], v[82:85], v[74:77], v[18:33]
	s_waitcnt lgkmcnt(0)
	v_mfma_f32_32x32x16_bf16 v[2:17], v[86:89], v[74:77], v[2:17]
	s_setprio 0
	ds_read_b128 v[66:69], v174 offset:17504
	ds_read_b128 v[70:73], v174 offset:22112
	ds_read_b128 v[74:77], v174 offset:26720
	ds_read_b128 v[82:85], v174 offset:31328
	s_setprio 1
	s_waitcnt lgkmcnt(3)
	v_mfma_f32_32x32x16_bf16 v[50:65], v[66:69], v[78:81], v[50:65]
	s_waitcnt lgkmcnt(2)
	v_mfma_f32_32x32x16_bf16 v[34:49], v[70:73], v[78:81], v[34:49]
	s_waitcnt lgkmcnt(1)
	v_mfma_f32_32x32x16_bf16 v[18:33], v[74:77], v[78:81], v[18:33]
	s_waitcnt lgkmcnt(0)
	v_mfma_f32_32x32x16_bf16 v[2:17], v[82:85], v[78:81], v[2:17]
	s_setprio 0
	v_not_b32_e32 v66, v218
	v_not_b32_e32 v82, v205
	v_bfe_i32 v83, v66, 0, 1
	v_bfe_i32 v174, v82, 0, 1
	v_bfe_i32 v67, v66, 1, 1
	v_bfe_i32 v175, v82, 1, 1
	v_bfe_i32 v68, v66, 2, 1
	v_bfe_i32 v84, v82, 2, 1
	v_bfe_i32 v69, v66, 3, 1
	v_bfe_i32 v85, v82, 3, 1
	v_bfe_i32 v70, v66, 8, 1
	v_bfe_i32 v86, v82, 8, 1
	v_bfe_i32 v71, v66, 9, 1
	v_bfe_i32 v87, v82, 9, 1
	v_bfe_i32 v72, v66, 10, 1
	v_bfe_i32 v88, v82, 10, 1
	v_bfe_i32 v73, v66, 11, 1
	v_bfe_i32 v89, v82, 11, 1
	v_bfe_i32 v74, v66, 16, 1
	v_bfe_i32 v90, v82, 16, 1
	v_bfe_i32 v75, v66, 17, 1
	v_bfe_i32 v91, v82, 17, 1
	v_bfe_i32 v76, v66, 18, 1
	v_bfe_i32 v92, v82, 18, 1
	v_bfe_i32 v77, v66, 19, 1
	v_bfe_i32 v93, v82, 19, 1
	v_bfe_i32 v78, v66, 24, 1
	v_bfe_i32 v94, v82, 24, 1
	v_bfe_i32 v79, v66, 25, 1
	v_bfe_i32 v95, v82, 25, 1
	v_bfe_i32 v80, v66, 26, 1
	v_bfe_i32 v96, v82, 26, 1
	v_bfe_i32 v66, v66, 27, 1
	v_bfe_i32 v82, v82, 27, 1
	s_nop 0
	v_and_b32_e32 v79, 0xff800000, v79
	v_and_b32_e32 v81, 0xff800000, v66
	v_and_b32_e32 v66, 0xff800000, v83
	v_and_b32_e32 v97, 0xff800000, v82
	v_and_b32_e32 v83, 0xff800000, v175
	v_and_b32_e32 v82, 0xff800000, v174
	ds_read_b128 v[174:177], v217 offset:8704
	ds_read_b128 v[218:221], v217
	ds_read_b128 v[222:225], v217 offset:32
	ds_read_b128 v[226:229], v217 offset:8736
	ds_read_b128 v[232:235], v217 offset:64
	ds_read_b128 v[236:239], v217 offset:8768
	ds_read_b128 v[240:243], v217 offset:96
	ds_read_b128 v[248:251], v217 offset:8800
	v_and_b32_e32 v80, 0xff800000, v80
	v_and_b32_e32 v78, 0xff800000, v78
	v_and_b32_e32 v77, 0xff800000, v77
	v_and_b32_e32 v76, 0xff800000, v76
	v_and_b32_e32 v75, 0xff800000, v75
	v_and_b32_e32 v74, 0xff800000, v74
	v_and_b32_e32 v73, 0xff800000, v73
	v_and_b32_e32 v72, 0xff800000, v72
	v_and_b32_e32 v71, 0xff800000, v71
	v_and_b32_e32 v70, 0xff800000, v70
	v_and_b32_e32 v69, 0xff800000, v69
	v_and_b32_e32 v68, 0xff800000, v68
	v_and_b32_e32 v67, 0xff800000, v67
	v_and_b32_e32 v96, 0xff800000, v96
	v_and_b32_e32 v95, 0xff800000, v95
	v_and_b32_e32 v94, 0xff800000, v94
	v_and_b32_e32 v93, 0xff800000, v93
	v_and_b32_e32 v92, 0xff800000, v92
	v_and_b32_e32 v91, 0xff800000, v91
	v_and_b32_e32 v90, 0xff800000, v90
	v_and_b32_e32 v89, 0xff800000, v89
	v_and_b32_e32 v88, 0xff800000, v88
	v_and_b32_e32 v87, 0xff800000, v87
	v_and_b32_e32 v86, 0xff800000, v86
	v_and_b32_e32 v85, 0xff800000, v85
	v_and_b32_e32 v84, 0xff800000, v84
	s_setprio 1
	s_waitcnt lgkmcnt(6)
	v_mfma_f32_32x32x16_bf16 v[66:81], v[218:221], v[98:101], v[66:81]
	v_mfma_f32_32x32x16_bf16 v[82:97], v[174:177], v[98:101], v[82:97]
	s_waitcnt lgkmcnt(5)
	v_mfma_f32_32x32x16_bf16 v[66:81], v[222:225], v[102:105], v[66:81]
	s_waitcnt lgkmcnt(4)
	v_mfma_f32_32x32x16_bf16 v[82:97], v[226:229], v[102:105], v[82:97]
	s_waitcnt lgkmcnt(3)
	v_mfma_f32_32x32x16_bf16 v[66:81], v[232:235], v[106:109], v[66:81]
	s_waitcnt lgkmcnt(2)
	v_mfma_f32_32x32x16_bf16 v[82:97], v[236:239], v[106:109], v[82:97]
	s_waitcnt lgkmcnt(1)
	v_mfma_f32_32x32x16_bf16 v[66:81], v[240:243], v[110:113], v[66:81]
	s_waitcnt lgkmcnt(0)
	v_mfma_f32_32x32x16_bf16 v[82:97], v[248:251], v[110:113], v[82:97]
	s_setprio 0
	ds_read_b128 v[174:177], v217 offset:128
	ds_read_b128 v[218:221], v217 offset:160
	ds_read_b128 v[222:225], v217 offset:8832
	ds_read_b128 v[226:229], v217 offset:8864
	ds_read_b128 v[232:235], v217 offset:192
	ds_read_b128 v[236:239], v217 offset:224
	ds_read_b128 v[240:243], v217 offset:8896
	ds_read_b128 v[248:251], v217 offset:8928
	s_setprio 1
	s_waitcnt lgkmcnt(7)
	v_mfma_f32_32x32x16_bf16 v[66:81], v[174:177], v[114:117], v[66:81]
	s_waitcnt lgkmcnt(5)
	v_mfma_f32_32x32x16_bf16 v[82:97], v[222:225], v[114:117], v[82:97]
	v_mfma_f32_32x32x16_bf16 v[66:81], v[218:221], v[118:121], v[66:81]
	s_waitcnt lgkmcnt(4)
	v_mfma_f32_32x32x16_bf16 v[82:97], v[226:229], v[118:121], v[82:97]
	s_waitcnt lgkmcnt(3)
	v_mfma_f32_32x32x16_bf16 v[66:81], v[232:235], v[122:125], v[66:81]
	s_waitcnt lgkmcnt(1)
	v_mfma_f32_32x32x16_bf16 v[82:97], v[240:243], v[122:125], v[82:97]
	v_mfma_f32_32x32x16_bf16 v[66:81], v[236:239], v[126:129], v[66:81]
	s_waitcnt lgkmcnt(0)
	v_mfma_f32_32x32x16_bf16 v[82:97], v[248:251], v[126:129], v[82:97]
	s_setprio 0
	s_or_b64 exec, exec, s[0:1]
	s_and_b64 vcc, exec, s[8:9]
	s_cbranch_vccz .LBB0_88
	s_branch .LBB0_89
